# grid barrier: arriver number nloc/2 of each XCD issues one background buffer_wbl2 (no wait) so the leader release flush has less dirty data
# baseline (speedup 1.0000x reference)
; DI unsigned xb_ld(unsigned* p) { return __hip_atomic_load(p, __ATOMIC_RELAXED, __HIP_MEMORY_SCOPE_AGENT); }
; DI unsigned xb_add(unsigned* p, unsigned v) { return __hip_atomic_fetch_add(p, v, __ATOMIC_RELAXED, __HIP_MEMORY_SCOPE_AGENT); }
; #define XB_SPIN(cond, bar) do { unsigned _sp = 0; while (cond) { __builtin_amdgcn_s_sleep(1); \
;     if ((++_sp & 255u) == 0u) { if (xb_ld(&(bar)[XB_TMO])) break; if (_sp > XB_SPIN_CAP) { atomicAdd(&(bar)[XB_TMO], 1u); break; } } } } while (0)
; DI void xcd_barrier(const XcdBarrier& b) {
;     ...
;     const unsigned old = xb_add(&bar[XB_XSUB(b.x)], 1u);
;     const unsigned gen = old / nloc;
;     if (old + 1u == (gen + 1u) * nloc) {
;       __builtin_amdgcn_fence(__ATOMIC_RELEASE, "agent");
;       asm volatile("s_waitcnt vmcnt(0)" ::: "memory");
;       const unsigned og = xb_add(&bar[XB_TOP], 1u);
;       const unsigned tg = og / nx;
;       if (og + 1u == (tg + 1u) * nx) xb_add(&bar[XB_TOPGEN], 1u);
;       else XB_SPIN(xb_ld(&bar[XB_TOPGEN]) == tg, bar);
;       __builtin_amdgcn_fence(__ATOMIC_ACQUIRE, "agent");
;       xb_add(&bar[XB_XGEN(b.x)], 1u);
;       asm volatile("s_waitcnt vmcnt(0)" ::: "memory");
;     } else {
;       XB_SPIN(xb_ld(&bar[XB_XGEN(b.x)]) == gen, bar);
.LBB0_508:
	s_or_b64 exec, exec, s[2:3]
	v_cvt_f32_u32_e32 v5, v3
	s_waitcnt vmcnt(0)
	v_readfirstlane_b32 s2, v4
	buffer_inv sc1
	v_sub_u32_e32 v4, 0, v3
	v_rcp_iflag_f32_e32 v5, v5
	v_add_u32_e32 v6, s2, v1
	v_mul_f32_e32 v5, 0x4f7ffffe, v5
	v_cvt_u32_f32_e32 v5, v5
	v_mul_lo_u32 v1, v4, v5
	v_mul_hi_u32 v1, v5, v1
	v_add_u32_e32 v1, v5, v1
	v_mul_hi_u32 v1, v6, v1
	v_mul_lo_u32 v4, v1, v3
	v_sub_u32_e32 v4, v6, v4
	v_add_u32_e32 v5, 1, v1
	v_cmp_ge_u32_e32 vcc, v4, v3
	s_nop 1
	v_cndmask_b32_e32 v1, v1, v5, vcc
	v_sub_u32_e32 v5, v4, v3
	v_cndmask_b32_e32 v4, v4, v5, vcc
	v_add_u32_e32 v5, 1, v1
	v_cmp_ge_u32_e32 vcc, v4, v3
	v_add_u32_e32 v4, 1, v6
	s_nop 0
	v_cndmask_b32_e32 v1, v1, v5, vcc
	v_mul_lo_u32 v5, v3, v1
	v_sub_u32_e32 v7, v6, v5
	v_lshrrev_b32_e32 v8, 1, v3
	s_nop 0
	v_readfirstlane_b32 s100, v7
	v_readfirstlane_b32 s101, v8
	s_cmp_lg_u32 s100, s101
	s_cbranch_scc1 .Lnoflush_0
	buffer_wbl2 sc1
.Lnoflush_0:
	v_add_u32_e32 v3, v5, v3
	v_cmp_ne_u32_e32 vcc, v4, v3
	s_and_saveexec_b64 s[2:3], vcc
	s_xor_b64 s[2:3], exec, s[2:3]
	s_cbranch_execz .LBB0_522
	v_readlane_b32 s4, v253, 21
	v_readlane_b32 s5, v253, 22
	s_waitcnt lgkmcnt(0)
	s_nop 3
	global_load_dword v0, v2, s[4:5] sc1
	s_waitcnt vmcnt(0)
	v_cmp_eq_u32_e32 vcc, v0, v1
	s_and_saveexec_b64 s[4:5], vcc
	s_cbranch_execz .LBB0_521
	s_mov_b32 s7, 1
	s_mov_b64 s[12:13], 0
	s_branch .LBB0_512

; DI unsigned xb_ld(unsigned* p) { return __hip_atomic_load(p, __ATOMIC_RELAXED, __HIP_MEMORY_SCOPE_AGENT); }
; DI unsigned xb_add(unsigned* p, unsigned v) { return __hip_atomic_fetch_add(p, v, __ATOMIC_RELAXED, __HIP_MEMORY_SCOPE_AGENT); }
; #define XB_SPIN(cond, bar) do { unsigned _sp = 0; while (cond) { __builtin_amdgcn_s_sleep(1); \
;     if ((++_sp & 255u) == 0u) { if (xb_ld(&(bar)[XB_TMO])) break; if (_sp > XB_SPIN_CAP) { atomicAdd(&(bar)[XB_TMO], 1u); break; } } } } while (0)
; DI void xcd_barrier(const XcdBarrier& b) {
;     ...
;     if (old + 1u == (gen + 1u) * nloc) {
;       __builtin_amdgcn_fence(__ATOMIC_RELEASE, "agent");
;       asm volatile("s_waitcnt vmcnt(0)" ::: "memory");
;       const unsigned og = xb_add(&bar[XB_TOP], 1u);
;       const unsigned tg = og / nx;
;       if (og + 1u == (tg + 1u) * nx) xb_add(&bar[XB_TOPGEN], 1u);
;       else XB_SPIN(xb_ld(&bar[XB_TOPGEN]) == tg, bar);
;       __builtin_amdgcn_fence(__ATOMIC_ACQUIRE, "agent");
;       xb_add(&bar[XB_XGEN(b.x)], 1u);
;       asm volatile("s_waitcnt vmcnt(0)" ::: "memory");
;     } else {
;       XB_SPIN(xb_ld(&bar[XB_XGEN(b.x)]) == gen, bar);
.Lnoflush_1:
	v_add_u32_e32 v3, v5, v3
	v_cmp_ne_u32_e32 vcc, v4, v3
	s_and_saveexec_b64 s[2:3], vcc
	s_xor_b64 s[2:3], exec, s[2:3]
	s_cbranch_execz .LBB0_610
	v_readlane_b32 s4, v253, 21
	v_readlane_b32 s5, v253, 22
	s_waitcnt lgkmcnt(0)
	s_nop 3
	global_load_dword v0, v2, s[4:5] sc1
	s_waitcnt vmcnt(0)
	v_cmp_eq_u32_e32 vcc, v0, v1
	s_and_saveexec_b64 s[4:5], vcc
	s_cbranch_execz .LBB0_609
	s_mov_b32 s7, 1
	s_mov_b64 s[8:9], 0
	s_branch .LBB0_600

; DI unsigned xb_ld(unsigned* p) { return __hip_atomic_load(p, __ATOMIC_RELAXED, __HIP_MEMORY_SCOPE_AGENT); }
; DI unsigned xb_add(unsigned* p, unsigned v) { return __hip_atomic_fetch_add(p, v, __ATOMIC_RELAXED, __HIP_MEMORY_SCOPE_AGENT); }
; #define XB_SPIN(cond, bar) do { unsigned _sp = 0; while (cond) { __builtin_amdgcn_s_sleep(1); \
;     if ((++_sp & 255u) == 0u) { if (xb_ld(&(bar)[XB_TMO])) break; if (_sp > XB_SPIN_CAP) { atomicAdd(&(bar)[XB_TMO], 1u); break; } } } } while (0)
; DI void xcd_barrier(const XcdBarrier& b) {
;     ...
;     if (old + 1u == (gen + 1u) * nloc) {
;       __builtin_amdgcn_fence(__ATOMIC_RELEASE, "agent");
;       asm volatile("s_waitcnt vmcnt(0)" ::: "memory");
;       const unsigned og = xb_add(&bar[XB_TOP], 1u);
;       const unsigned tg = og / nx;
;       if (og + 1u == (tg + 1u) * nx) xb_add(&bar[XB_TOPGEN], 1u);
;       else XB_SPIN(xb_ld(&bar[XB_TOPGEN]) == tg, bar);
;       __builtin_amdgcn_fence(__ATOMIC_ACQUIRE, "agent");
;       xb_add(&bar[XB_XGEN(b.x)], 1u);
;       asm volatile("s_waitcnt vmcnt(0)" ::: "memory");
;     } else {
;       XB_SPIN(xb_ld(&bar[XB_XGEN(b.x)]) == gen, bar);
.Lnoflush_2:
	v_add_u32_e32 v3, v5, v3
	v_cmp_ne_u32_e32 vcc, v4, v3
	s_and_saveexec_b64 s[2:3], vcc
	s_xor_b64 s[2:3], exec, s[2:3]
	s_cbranch_execz .LBB0_882
	v_readlane_b32 s4, v253, 21
	v_readlane_b32 s5, v253, 22
	s_waitcnt lgkmcnt(0)
	s_nop 3
	global_load_dword v0, v2, s[4:5] sc1
	s_waitcnt vmcnt(0)
	v_cmp_eq_u32_e32 vcc, v0, v1
	s_and_saveexec_b64 s[4:5], vcc
	s_cbranch_execz .LBB0_881
	s_mov_b32 s24, 1
	s_mov_b64 s[6:7], 0
	s_branch .LBB0_872

; __global__ void __launch_bounds__(512, 2) mega(Params p) {
	.amdhsa_kernel _Z4mega6Params
		.amdhsa_group_segment_fixed_size 136208
		.amdhsa_private_segment_fixed_size 0
		.amdhsa_kernarg_size 464
		.amdhsa_user_sgpr_count 2
		.amdhsa_user_sgpr_dispatch_ptr 0
		.amdhsa_user_sgpr_queue_ptr 0
		.amdhsa_user_sgpr_kernarg_segment_ptr 1
		.amdhsa_user_sgpr_dispatch_id 0
		.amdhsa_user_sgpr_kernarg_preload_length 0
		.amdhsa_user_sgpr_kernarg_preload_offset 0
		.amdhsa_user_sgpr_private_segment_size 0
		.amdhsa_uses_dynamic_stack 0
		.amdhsa_enable_private_segment 0
		.amdhsa_system_sgpr_workgroup_id_x 1
		.amdhsa_system_sgpr_workgroup_id_y 0
		.amdhsa_system_sgpr_workgroup_id_z 0
		.amdhsa_system_sgpr_workgroup_info 0
		.amdhsa_system_vgpr_workitem_id 2
		.amdhsa_next_free_vgpr 256
		.amdhsa_next_free_sgpr 102
		.amdhsa_accum_offset 256
		.amdhsa_reserve_vcc 1
		.amdhsa_float_round_mode_32 0
		.amdhsa_float_round_mode_16_64 0
		.amdhsa_float_denorm_mode_32 3
		.amdhsa_float_denorm_mode_16_64 3
		.amdhsa_dx10_clamp 1
		.amdhsa_ieee_mode 1
		.amdhsa_fp16_overflow 0
		.amdhsa_tg_split 0
		.amdhsa_exception_fp_ieee_invalid_op 0
		.amdhsa_exception_fp_denorm_src 0
		.amdhsa_exception_fp_ieee_div_zero 0
		.amdhsa_exception_fp_ieee_overflow 0
		.amdhsa_exception_fp_ieee_underflow 0
		.amdhsa_exception_fp_ieee_inexact 0
		.amdhsa_exception_int_div_zero 0
	.end_amdhsa_kernel

; __global__ void __launch_bounds__(512, 2) mega(Params p) {
amdhsa.kernels:
  - .agpr_count:     0
    .args:
      - .offset:         0
        .size:           208
        .value_kind:     by_value
      - .offset:         208
        .size:           4
        .value_kind:     hidden_block_count_x
      - .offset:         212
        .size:           4
        .value_kind:     hidden_block_count_y
      - .offset:         216
        .size:           4
        .value_kind:     hidden_block_count_z
      - .offset:         220
        .size:           2
        .value_kind:     hidden_group_size_x
      - .offset:         222
        .size:           2
        .value_kind:     hidden_group_size_y
      - .offset:         224
        .size:           2
        .value_kind:     hidden_group_size_z
      - .offset:         226
        .size:           2
        .value_kind:     hidden_remainder_x
      - .offset:         228
        .size:           2
        .value_kind:     hidden_remainder_y
      - .offset:         230
        .size:           2
        .value_kind:     hidden_remainder_z
      - .offset:         248
        .size:           8
        .value_kind:     hidden_global_offset_x
      - .offset:         256
        .size:           8
        .value_kind:     hidden_global_offset_y
      - .offset:         264
        .size:           8
        .value_kind:     hidden_global_offset_z
      - .offset:         272
        .size:           2
        .value_kind:     hidden_grid_dims
      - .offset:         296
        .size:           8
        .value_kind:     hidden_multigrid_sync_arg
    .group_segment_fixed_size: 136208
    .kernarg_segment_align: 8
    .kernarg_segment_size: 464
    .language:       OpenCL C
    .language_version:
      - 2
      - 0
    .max_flat_workgroup_size: 512
    .name:           _Z4mega6Params
    .private_segment_fixed_size: 0
    .sgpr_count:     108
    .sgpr_spill_count: 212
    .symbol:         _Z4mega6Params.kd
    .uniform_work_group_size: 1
    .uses_dynamic_stack: false
    .vgpr_count:     256
    .vgpr_spill_count: 0
    .wavefront_size: 64
